# norm2, layer-1 norm1 and final norm take rows panel-wise: each workgroup normalises the 256-row panels its own GEMM tiles cover (same XCD L2)
# speedup vs baseline: 1.0038x; 1.0016x over previous
.LBB0_16:
	s_cmp_eq_u32 s80, 19
	s_mov_b64 s[0:1], -1
	s_cbranch_scc0 .LBB0_22
	s_waitcnt vmcnt(0)
	v_mov_b32_e32 v0, v200
	s_load_dword s0, s[38:39], 0x0
	v_ashrrev_i32_e32 v2, 6, v0
	v_add_u32_e32 v49, s61, v2
	v_sub_u32_e32 v2, 0, v49
	v_max_i32_e32 v2, v49, v2
	s_waitcnt lgkmcnt(0)
	s_bfe_i32 s19, s0, 0x1d0000
	s_abs_i32 s1, s19
	v_cvt_f32_u32_e32 v1, s1
	v_xor_b32_e32 v3, s19, v49
	s_sub_i32 s6, 0, s1
	v_ashrrev_i32_e32 v50, 31, v3
	v_rcp_iflag_f32_e32 v1, v1
	s_mov_b32 s20, 0x800000
	v_mul_f32_e32 v1, 0x4f7ffffe, v1
	v_cvt_u32_f32_e32 v1, v1
	v_mul_lo_u32 v3, s6, v1
	v_mul_hi_u32 v3, v1, v3
	v_add_u32_e32 v1, v1, v3
	v_mul_hi_u32 v1, v2, v1
	v_mul_lo_u32 v3, v1, s1
	v_sub_u32_e32 v2, v2, v3
	v_add_u32_e32 v4, 1, v1
	v_cmp_le_u32_e32 vcc, s1, v2
	v_subrev_u32_e32 v3, s1, v2
	s_nop 0
	v_cndmask_b32_e32 v1, v1, v4, vcc
	v_cndmask_b32_e32 v2, v2, v3, vcc
	v_add_u32_e32 v3, 1, v1
	v_cmp_le_u32_e32 vcc, s1, v2
	s_nop 1
	v_cndmask_b32_e32 v1, v1, v3, vcc
	v_xor_b32_e32 v51, v1, v50
	v_sub_u32_e32 v16, v51, v50
	s_bfe_u32 s100, s61, 0x30003
	v_mov_b32_e32 v16, s100
	v_cmp_gt_i32_e32 vcc, 8, v16
	s_and_saveexec_b64 s[6:7], vcc
	s_cbranch_execz .LBB0_21
	v_lshlrev_b32_e32 v1, 12, v16
	v_mul_lo_u32 v2, v16, s19
	v_add_u32_e32 v3, v1, v49
	v_sub_u32_e32 v48, v3, v2
	v_add_u32_e32 v72, 0x1000, v1
	s_lshr_b32 s101, s61, 6
	s_and_b32 s100, s101, 7
	s_lshr_b32 s101, s101, 3
	s_lshl_b32 s100, s100, 8
	s_lshl_b32 s101, s101, 3
	s_add_i32 s101, s101, s100
	s_bfe_u32 s100, s61, 0x30003
	s_lshl_b32 s100, s100, 12
	s_add_i32 s101, s101, s100
	s_mov_b32 s100, 0
	v_lshrrev_b32_e32 v48, 6, v200
	v_add_u32_e32 v48, s101, v48
	v_and_b32_e32 v72, 0xffffff00, v48
	v_add_u32_e32 v72, 0x100, v72
	v_cmp_lt_i32_e32 vcc, v48, v72
	s_and_b64 exec, exec, vcc
	s_cbranch_execz .LBB0_21
	v_readlane_b32 s12, v253, 4
	v_readlane_b32 s13, v253, 5
	v_and_b32_e32 v52, 63, v0
	v_lshlrev_b32_e32 v128, 4, v52
	v_mov_b64_e32 v[18:19], s[12:13]
	v_mad_i64_i32 v[18:19], s[12:13], v16, s84, v[18:19]
	v_readlane_b32 s12, v253, 2
	v_readlane_b32 s13, v253, 3
	v_lshl_add_u64 v[36:37], v[18:19], 0, v[128:129]
	global_load_dwordx4 v[0:3], v128, s[74:75]
	global_load_dwordx4 v[4:7], v128, s[74:75] offset:1024
	global_load_dwordx4 v[8:11], v128, s[74:75] offset:2048
	global_load_dwordx4 v[12:15], v128, s[74:75] offset:3072
	v_mov_b64_e32 v[18:19], s[12:13]
	v_mad_i64_i32 v[16:17], s[12:13], v16, s84, v[18:19]
	v_lshl_add_u64 v[44:45], v[16:17], 0, v[128:129]
	global_load_dwordx4 v[16:19], v[36:37], off offset:3072
	global_load_dwordx4 v[20:23], v[36:37], off offset:2048
	global_load_dwordx4 v[24:27], v[44:45], off offset:3072
	global_load_dwordx4 v[28:31], v[44:45], off offset:2048
	global_load_dwordx4 v[32:35], v[36:37], off offset:1024
	s_nop 0
	global_load_dwordx4 v[36:39], v[36:37], off
	s_nop 0
	global_load_dwordx4 v[40:43], v[44:45], off offset:1024
	s_nop 0
	global_load_dwordx4 v[44:47], v[44:45], off
	v_cmp_lt_i32_e32 vcc, v206, v205
	v_readlane_b32 s14, v254, 58
	s_mov_b32 s1, 0
	v_cndmask_b32_e32 v53, v204, v206, vcc
	v_cmp_lt_i32_e32 vcc, v207, v205
	v_lshlrev_b32_e32 v73, 2, v53
	s_mov_b32 s0, 32
	v_cndmask_b32_e32 v53, v204, v207, vcc
	v_cmp_lt_i32_e32 vcc, v252, v205
	v_lshlrev_b32_e32 v74, 2, v53
	v_readlane_b32 s15, v254, 59
	v_cndmask_b32_e32 v53, v204, v252, vcc
	v_lshlrev_b32_e32 v75, 2, v53
	v_xor_b32_e32 v53, 8, v204
	v_cmp_lt_i32_e32 vcc, v53, v205
	s_lshl_b64 s[12:13], s[0:1], 11
	s_mov_b64 s[16:17], 0
	v_cndmask_b32_e32 v53, v204, v53, vcc
	v_cmp_lt_i32_e32 vcc, v210, v205
	v_lshlrev_b32_e32 v76, 2, v53
	s_nop 0
	v_cndmask_b32_e32 v53, v204, v210, vcc
	v_cmp_lt_i32_e32 vcc, v211, v205
	v_lshlrev_b32_e32 v77, 2, v53
	s_nop 0
	v_cndmask_b32_e32 v53, v204, v211, vcc
	v_lshlrev_b32_e32 v78, 2, v53
	v_sub_u32_e32 v53, v50, v51
	v_mul_lo_u32 v53, v53, s19
	v_lshlrev_b32_e32 v51, 12, v51
	v_add3_u32 v49, v49, v53, v51
	v_lshlrev_b32_e32 v50, 12, v50
	v_sub_u32_e32 v79, v49, v50
	v_mov_b32_e32 v79, v48
	v_ashrrev_i32_e32 v49, 31, v48
	v_lshlrev_b64 v[50:51], 11, v[48:49]
	v_lshlrev_b64 v[48:49], 12, v[48:49]
	v_lshl_or_b32 v50, v52, 3, v50
	v_or_b32_e32 v48, v48, v128
	v_lshl_add_u64 v[64:65], s[4:5], 0, v[50:51]
	v_lshl_add_u64 v[66:67], s[14:15], 0, v[48:49]
	s_lshl_b64 s[14:15], s[0:1], 12
.LBB0_20:
	global_load_dwordx2 v[80:81], v[64:65], off nt
	global_load_dwordx2 v[68:69], v[64:65], off offset:512 nt
	global_load_dwordx4 v[52:55], v[66:67], off offset:-3072 nt
	global_load_dwordx4 v[48:51], v[66:67], off offset:-2048 nt
	global_load_dwordx2 v[70:71], v[64:65], off offset:1024 nt
	global_load_dwordx4 v[60:63], v[66:67], off offset:-1024 nt
	global_load_dwordx4 v[56:59], v[66:67], off nt
	global_load_dwordx2 v[82:83], v[64:65], off offset:1536 nt
	v_add_co_u32_e32 v84, vcc, 0xec800000, v64
	v_add_co_u32_e64 v86, s[0:1], s60, v64
	s_nop 0
	v_addc_co_u32_e32 v85, vcc, -1, v65, vcc
	v_addc_co_u32_e64 v87, s[0:1], -1, v65, s[0:1]
	global_load_dwordx2 v[84:85], v[84:85], off nt
	s_nop 0
	global_load_dwordx2 v[88:89], v[86:87], off offset:-3584 nt
	global_load_dwordx2 v[90:91], v[86:87], off offset:-3072 nt
	s_nop 0
	global_load_dwordx2 v[86:87], v[86:87], off offset:-2560 nt
	v_add_u32_e32 v79, 32, v79
	v_cmp_ge_i32_e32 vcc, v79, v72
	s_or_b64 s[16:17], vcc, s[16:17]
	v_lshl_add_u64 v[64:65], v[64:65], 0, s[12:13]
	s_waitcnt vmcnt(11)
	v_lshlrev_b32_e32 v92, 16, v80
	v_and_b32_e32 v93, 0xffff0000, v80
	v_lshlrev_b32_e32 v80, 16, v81
	v_and_b32_e32 v81, 0xffff0000, v81
	s_waitcnt vmcnt(10)
	v_lshlrev_b32_e32 v94, 16, v68
	v_and_b32_e32 v95, 0xffff0000, v68
	v_lshlrev_b32_e32 v68, 16, v69
	v_and_b32_e32 v69, 0xffff0000, v69
	s_waitcnt vmcnt(7)
	v_lshlrev_b32_e32 v96, 16, v70
	v_and_b32_e32 v97, 0xffff0000, v70
	v_lshlrev_b32_e32 v70, 16, v71
	v_and_b32_e32 v71, 0xffff0000, v71
	s_waitcnt vmcnt(4)
	v_lshlrev_b32_e32 v98, 16, v82
	v_and_b32_e32 v99, 0xffff0000, v82
	v_lshlrev_b32_e32 v82, 16, v83
	v_and_b32_e32 v83, 0xffff0000, v83
	v_pk_fma_f32 v[52:53], v[44:45], v[92:93], v[52:53]
	v_pk_fma_f32 v[54:55], v[46:47], v[80:81], v[54:55]
	v_pk_fma_f32 v[48:49], v[40:41], v[94:95], v[48:49]
	v_pk_fma_f32 v[50:51], v[42:43], v[68:69], v[50:51]
	v_pk_fma_f32 v[62:63], v[30:31], v[70:71], v[62:63]
	v_pk_fma_f32 v[58:59], v[26:27], v[82:83], v[58:59]
	s_waitcnt vmcnt(3)
	v_lshlrev_b32_e32 v68, 16, v84
	v_and_b32_e32 v69, 0xffff0000, v84
	v_lshlrev_b32_e32 v70, 16, v85
	v_and_b32_e32 v71, 0xffff0000, v85
	s_waitcnt vmcnt(2)
	v_lshlrev_b32_e32 v80, 16, v88
	v_and_b32_e32 v81, 0xffff0000, v88
	v_lshlrev_b32_e32 v82, 16, v89
	v_and_b32_e32 v83, 0xffff0000, v89
	v_pk_fma_f32 v[52:53], v[36:37], v[68:69], v[52:53]
	v_pk_fma_f32 v[54:55], v[38:39], v[70:71], v[54:55]
	v_pk_fma_f32 v[48:49], v[32:33], v[80:81], v[48:49]
	v_pk_fma_f32 v[50:51], v[34:35], v[82:83], v[50:51]
	v_pk_fma_f32 v[60:61], v[28:29], v[96:97], v[60:61]
	s_waitcnt vmcnt(1)
	v_lshlrev_b32_e32 v84, 16, v90
	v_and_b32_e32 v85, 0xffff0000, v90
	v_lshlrev_b32_e32 v88, 16, v91
	v_and_b32_e32 v89, 0xffff0000, v91
	v_mov_b32_e32 v70, v53
	v_mov_b32_e32 v71, v55
	v_mov_b32_e32 v82, v49
	v_mov_b32_e32 v83, v51
	v_pk_fma_f32 v[56:57], v[24:25], v[98:99], v[56:57]
	s_waitcnt vmcnt(0)
	v_lshlrev_b32_e32 v90, 16, v86
	v_and_b32_e32 v91, 0xffff0000, v86
	v_lshlrev_b32_e32 v86, 16, v87
	v_and_b32_e32 v87, 0xffff0000, v87
	v_pk_fma_f32 v[60:61], v[20:21], v[84:85], v[60:61]
	v_pk_fma_f32 v[62:63], v[22:23], v[88:89], v[62:63]
	v_mov_b32_e32 v68, v52
	v_mov_b32_e32 v69, v54
	v_mov_b32_e32 v80, v48
	v_mov_b32_e32 v81, v50
	v_pk_mul_f32 v[70:71], v[70:71], v[70:71]
	v_pk_mul_f32 v[82:83], v[82:83], v[82:83]
	v_pk_fma_f32 v[56:57], v[16:17], v[90:91], v[56:57]
	v_pk_fma_f32 v[58:59], v[18:19], v[86:87], v[58:59]
	v_mul_f32_e32 v84, v61, v61
	v_mul_f32_e32 v86, v63, v63
	v_pk_fma_f32 v[68:69], v[68:69], v[68:69], v[70:71]
	v_pk_fma_f32 v[70:71], v[80:81], v[80:81], v[82:83]
	v_pk_mul_f32 v[88:89], v[56:57], v[56:57]
	v_pk_mul_f32 v[90:91], v[58:59], v[58:59]
	v_pk_fma_f32 v[84:85], v[60:61], v[60:61], v[84:85] op_sel_hi:[1,1,0]
	v_pk_fma_f32 v[86:87], v[62:63], v[62:63], v[86:87] op_sel_hi:[1,1,0]
	v_pk_add_f32 v[68:69], v[68:69], v[68:69] op_sel:[0,1] op_sel_hi:[1,0]
	v_pk_add_f32 v[70:71], v[70:71], v[70:71] op_sel:[0,1] op_sel_hi:[1,0]
	v_mov_b32_e32 v85, v90
	v_mov_b32_e32 v87, v91
	v_mov_b32_e32 v69, v88
	v_mov_b32_e32 v71, v89
	v_pk_add_f32 v[80:81], v[84:85], v[86:87]
	v_pk_add_f32 v[68:69], v[68:69], v[70:71]
	s_nop 0
	v_pk_add_f32 v[68:69], v[68:69], v[80:81]
	s_nop 0
	v_add_f32_e32 v68, v68, v69
	ds_bpermute_b32 v69, v73, v68
	s_waitcnt lgkmcnt(0)
	v_add_f32_e32 v68, v68, v69
	ds_bpermute_b32 v69, v74, v68
	s_waitcnt lgkmcnt(0)
	v_add_f32_e32 v68, v68, v69
	ds_bpermute_b32 v69, v75, v68
	s_waitcnt lgkmcnt(0)
	v_add_f32_e32 v68, v68, v69
	ds_bpermute_b32 v69, v76, v68
	s_waitcnt lgkmcnt(0)
	v_add_f32_e32 v68, v68, v69
	ds_bpermute_b32 v69, v77, v68
	s_waitcnt lgkmcnt(0)
	v_add_f32_e32 v68, v68, v69
	ds_bpermute_b32 v69, v78, v68
	s_waitcnt lgkmcnt(0)
	v_add_f32_e32 v68, v68, v69
	v_fmamk_f32 v68, v68, 0x3a800000, v201
	v_mul_f32_e32 v69, 0x4b800000, v68
	v_cmp_gt_f32_e32 vcc, s20, v68
	s_nop 1
	v_cndmask_b32_e32 v68, v68, v69, vcc
	v_rsq_f32_e32 v68, v68
	s_nop 0
	v_mul_f32_e32 v69, 0x45800000, v68
	v_cndmask_b32_e32 v68, v68, v69, vcc
	v_pk_mul_f32 v[52:53], v[52:53], v[68:69] op_sel_hi:[1,0]
	v_pk_mul_f32 v[54:55], v[54:55], v[68:69] op_sel_hi:[1,0]
	v_pk_mul_f32 v[70:71], v[48:49], v[68:69] op_sel_hi:[1,0]
	v_pk_mul_f32 v[80:81], v[50:51], v[68:69] op_sel_hi:[1,0]
	v_pk_mul_f32 v[60:61], v[60:61], v[68:69] op_sel_hi:[1,0]
	v_pk_mul_f32 v[62:63], v[62:63], v[68:69] op_sel_hi:[1,0]
	v_pk_mul_f32 v[82:83], v[56:57], v[68:69] op_sel_hi:[1,0]
	v_pk_mul_f32 v[68:69], v[58:59], v[68:69] op_sel_hi:[1,0]
	v_pk_mul_f32 v[50:51], v[2:3], v[54:55]
	v_pk_mul_f32 v[48:49], v[0:1], v[52:53]
	v_pk_mul_f32 v[54:55], v[6:7], v[80:81]
	v_pk_mul_f32 v[52:53], v[4:5], v[70:71]
	v_pk_mul_f32 v[58:59], v[10:11], v[62:63]
	v_pk_mul_f32 v[56:57], v[8:9], v[60:61]
	v_pk_mul_f32 v[62:63], v[14:15], v[68:69]
	v_pk_mul_f32 v[60:61], v[12:13], v[82:83]
	global_store_dwordx4 v[66:67], v[48:51], off offset:-3072 nt
	global_store_dwordx4 v[66:67], v[52:55], off offset:-2048 nt
	global_store_dwordx4 v[66:67], v[56:59], off offset:-1024 nt
	global_store_dwordx4 v[66:67], v[60:63], off nt
	v_lshl_add_u64 v[66:67], v[66:67], 0, s[14:15]
	s_andn2_b64 exec, exec, s[16:17]
	s_cbranch_execnz .LBB0_20
	s_or_b64 exec, exec, s[16:17]
	s_cmp_lg_u32 s100, 0
	s_cbranch_scc1 .Lnt_done_f
	s_mov_b32 s100, 1
	s_mov_b64 s[16:17], 0
	v_add_u32_e32 v79, 0x700, v79
	v_add_u32_e32 v72, 0x800, v72
	s_mov_b32 vcc_lo, 0x380000
	s_mov_b32 vcc_hi, 0
	v_lshl_add_u64 v[64:65], v[64:65], 0, vcc
	s_mov_b32 vcc_lo, 0x700000
	v_lshl_add_u64 v[66:67], v[66:67], 0, vcc
	s_branch .LBB0_20
.Lnt_done_f:
.LBB0_21:
	s_or_b64 exec, exec, s[6:7]
	s_mov_b64 s[0:1], 0

.LBB0_112:
	s_andn2_b64 vcc, exec, s[2:3]
	s_cbranch_vccnz .LBB0_118
	s_waitcnt vmcnt(0)
	v_mov_b32_e32 v0, v200
	s_load_dword s2, s[38:39], 0x0
	v_ashrrev_i32_e32 v1, 6, v0
	v_add_u32_e32 v64, s61, v1
	s_waitcnt lgkmcnt(0)
	s_bfe_i32 s14, s2, 0x1d0000
	s_abs_i32 s0, s14
	v_cvt_f32_u32_e32 v2, s0
	s_sub_i32 s1, 0, s0
	v_xor_b32_e32 v1, s14, v64
	v_ashrrev_i32_e32 v65, 31, v1
	v_rcp_iflag_f32_e32 v2, v2
	v_sub_u32_e32 v1, 0, v64
	v_max_i32_e32 v1, v64, v1
	v_mul_f32_e32 v2, 0x4f7ffffe, v2
	v_cvt_u32_f32_e32 v2, v2
	v_mul_lo_u32 v3, s1, v2
	v_mul_hi_u32 v3, v2, v3
	v_add_u32_e32 v2, v2, v3
	v_mul_hi_u32 v2, v1, v2
	v_mul_lo_u32 v3, v2, s0
	v_sub_u32_e32 v1, v1, v3
	v_cmp_le_u32_e32 vcc, s0, v1
	v_add_u32_e32 v3, 1, v2
	s_nop 0
	v_cndmask_b32_e32 v2, v2, v3, vcc
	v_subrev_u32_e32 v3, s0, v1
	v_cndmask_b32_e32 v1, v1, v3, vcc
	v_cmp_le_u32_e32 vcc, s0, v1
	v_add_u32_e32 v1, 1, v2
	s_nop 0
	v_cndmask_b32_e32 v1, v2, v1, vcc
	v_xor_b32_e32 v67, v1, v65
	v_sub_u32_e32 v16, v67, v65
	s_bfe_u32 s100, s61, 0x30003
	v_mov_b32_e32 v16, s100
	v_cmp_gt_i32_e32 vcc, 8, v16
	s_and_saveexec_b64 s[0:1], vcc
	s_mov_b32 s16, 0x800000
	s_cbranch_execz .LBB0_117
	v_lshlrev_b32_e32 v1, 12, v16
	v_mul_lo_u32 v2, v16, s14
	v_add_u32_e32 v3, v1, v64
	v_sub_u32_e32 v66, v3, v2
	v_add_u32_e32 v77, 0x1000, v1
	s_lshr_b32 s101, s61, 6
	s_and_b32 s100, s101, 7
	s_lshr_b32 s101, s101, 3
	s_lshl_b32 s100, s100, 8
	s_lshl_b32 s101, s101, 3
	s_add_i32 s101, s101, s100
	s_bfe_u32 s100, s61, 0x30003
	s_lshl_b32 s100, s100, 12
	s_add_i32 s101, s101, s100
	s_mov_b32 s100, 0
	v_lshrrev_b32_e32 v66, 6, v200
	v_add_u32_e32 v66, s101, v66
	v_and_b32_e32 v77, 0xffffff00, v66
	v_add_u32_e32 v77, 0x100, v77
	v_cmp_lt_i32_e32 vcc, v66, v77
	s_and_b64 exec, exec, vcc
	s_cbranch_execz .LBB0_117
	v_readlane_b32 s6, v255, 29
	v_readlane_b32 s7, v255, 30
	s_lshl_b64 s[6:7], s[6:7], 2
	s_add_u32 s6, s68, s6
	v_and_b32_e32 v68, 63, v0
	s_addc_u32 s7, s69, s7
	v_lshlrev_b32_e32 v128, 4, v68
	global_load_dwordx4 v[0:3], v128, s[6:7]
	global_load_dwordx4 v[4:7], v128, s[6:7] offset:1024
	global_load_dwordx4 v[8:11], v128, s[6:7] offset:2048
	global_load_dwordx4 v[12:15], v128, s[6:7] offset:3072
	v_readlane_b32 s6, v255, 25
	v_readlane_b32 s7, v255, 26
	s_movk_i32 s3, 0x4000
	s_mov_b64 s[12:13], 0x2000
	v_mov_b64_e32 v[18:19], s[6:7]
	v_mad_i64_i32 v[16:17], s[6:7], v16, s84, v[18:19]
	v_lshl_add_u64 v[44:45], v[16:17], 0, v[128:129]
	v_add_co_u32_e32 v16, vcc, s3, v44
	s_movk_i32 s3, 0x3000
	s_nop 0
	v_addc_co_u32_e32 v17, vcc, 0, v45, vcc
	global_load_dwordx4 v[16:19], v[16:17], off
	s_mov_b64 s[6:7], 0x4000
	v_lshl_add_u64 v[28:29], v[44:45], 0, s[6:7]
	s_mov_b64 s[6:7], 0x3000
	v_lshl_add_u64 v[32:33], v[44:45], 0, s[6:7]
	v_lshl_add_u64 v[40:41], v[44:45], 0, s[12:13]
	s_and_b64 s[6:7], s[42:43], exec
	v_readlane_b32 s40, v254, 61
	v_readlane_b32 s41, v254, 62
	s_cselect_b32 s7, s41, s77
	s_cselect_b32 s6, s40, s76
	s_mov_b32 s13, 0
	s_mov_b32 s12, 32
	v_readlane_b32 s42, v254, 63
	v_readlane_b32 s43, v255, 0
	v_readlane_b32 s44, v255, 1
	v_readlane_b32 s45, v255, 2
	v_readlane_b32 s46, v255, 3
	v_readlane_b32 s47, v255, 4
	v_readlane_b32 s48, v255, 5
	v_readlane_b32 s49, v255, 6
	v_readlane_b32 s50, v255, 7
	v_readlane_b32 s51, v255, 8
	v_readlane_b32 s52, v255, 9
	v_readlane_b32 s53, v255, 10
	v_readlane_b32 s54, v255, 11
	v_readlane_b32 s55, v255, 12
	s_waitcnt vmcnt(0)
	v_pk_add_f32 v[50:51], v[16:17], 1.0 op_sel_hi:[1,0]
	v_add_co_u32_e32 v16, vcc, s3, v44
	v_pk_add_f32 v[48:49], v[18:19], 1.0 op_sel_hi:[1,0]
	s_nop 0
	v_addc_co_u32_e32 v17, vcc, 0, v45, vcc
	global_load_dwordx4 v[16:19], v[16:17], off
	s_nop 0
	global_load_dwordx4 v[20:23], v[28:29], off offset:1024
	s_movk_i32 s3, 0x2000
	v_add_co_u32_e32 v44, vcc, s3, v44
	s_lshl_b64 s[2:3], s[12:13], 11
	s_nop 0
	v_addc_co_u32_e32 v45, vcc, 0, v45, vcc
	v_cmp_lt_i32_e32 vcc, v206, v205
	s_waitcnt vmcnt(0)
	v_pk_add_f32 v[52:53], v[22:23], 1.0 op_sel_hi:[1,0]
	v_pk_add_f32 v[54:55], v[20:21], 1.0 op_sel_hi:[1,0]
	global_load_dwordx4 v[20:23], v[32:33], off offset:1024
	global_load_dwordx4 v[24:27], v[28:29], off offset:2048
	v_cndmask_b32_e32 v69, v204, v206, vcc
	v_cmp_lt_i32_e32 vcc, v207, v205
	v_lshlrev_b32_e32 v80, 2, v69
	s_waitcnt vmcnt(0)
	v_pk_add_f32 v[56:57], v[26:27], 1.0 op_sel_hi:[1,0]
	v_pk_add_f32 v[58:59], v[24:25], 1.0 op_sel_hi:[1,0]
	global_load_dwordx4 v[24:27], v[32:33], off offset:2048
	s_nop 0
	global_load_dwordx4 v[28:31], v[28:29], off offset:3072
	v_cndmask_b32_e32 v69, v204, v207, vcc
	v_cmp_lt_i32_e32 vcc, v252, v205
	v_lshlrev_b32_e32 v81, 2, v69
	s_waitcnt vmcnt(0)
	v_pk_add_f32 v[60:61], v[30:31], 1.0 op_sel_hi:[1,0]
	v_pk_add_f32 v[62:63], v[28:29], 1.0 op_sel_hi:[1,0]
	global_load_dwordx4 v[28:31], v[32:33], off offset:3072
	s_nop 0
	global_load_dwordx4 v[32:35], v[40:41], off offset:3072
	global_load_dwordx4 v[36:39], v[40:41], off offset:2048
	s_nop 0
	global_load_dwordx4 v[40:43], v[40:41], off offset:1024
	v_cndmask_b32_e32 v69, v204, v252, vcc
	global_load_dwordx4 v[44:47], v[44:45], off
	v_lshlrev_b32_e32 v82, 2, v69
	v_xor_b32_e32 v69, 8, v204
	v_cmp_lt_i32_e32 vcc, v69, v205
	s_nop 1
	v_cndmask_b32_e32 v69, v204, v69, vcc
	v_cmp_lt_i32_e32 vcc, v210, v205
	v_lshlrev_b32_e32 v83, 2, v69
	s_nop 0
	v_cndmask_b32_e32 v69, v204, v210, vcc
	v_cmp_lt_i32_e32 vcc, v211, v205
	v_lshlrev_b32_e32 v84, 2, v69
	s_nop 0
	v_cndmask_b32_e32 v69, v204, v211, vcc
	v_lshlrev_b32_e32 v85, 2, v69
	v_sub_u32_e32 v69, v65, v67
	v_mul_lo_u32 v69, v69, s14
	v_lshlrev_b32_e32 v67, 12, v67
	v_add3_u32 v64, v64, v69, v67
	v_lshlrev_b32_e32 v65, 12, v65
	v_ashrrev_i32_e32 v67, 31, v66
	v_sub_u32_e32 v86, v64, v65
	v_mov_b32_e32 v86, v66
	v_lshlrev_b64 v[64:65], 11, v[66:67]
	v_lshlrev_b64 v[66:67], 12, v[66:67]
	v_or_b32_e32 v66, v66, v128
	v_lshl_or_b32 v64, v68, 3, v64
	v_lshl_add_u64 v[66:67], s[6:7], 0, v[66:67]
	s_mov_b64 s[6:7], 0xc00
	v_lshl_add_u64 v[64:65], s[4:5], 0, v[64:65]
	v_lshl_add_u64 v[66:67], v[66:67], 0, s[6:7]
	s_lshl_b64 s[6:7], s[12:13], 12
	s_mov_b64 s[12:13], 0
.LBB0_116:
	global_load_dwordx4 v[68:71], v[66:67], off offset:-3072 nt
	global_load_dwordx4 v[72:75], v[66:67], off offset:-2048 nt
	global_load_dwordx4 v[88:91], v[66:67], off offset:-1024 nt
	global_load_dwordx4 v[92:95], v[66:67], off nt
	global_load_dwordx2 v[78:79], v[64:65], off nt
	s_mov_b32 s15, 0xec800000
	v_add_u32_e32 v86, 32, v86
	v_lshl_add_u64 v[66:67], v[66:67], 0, s[6:7]
	s_waitcnt vmcnt(0)
	v_lshlrev_b32_e32 v96, 16, v78
	v_and_b32_e32 v97, 0xffff0000, v78
	v_pk_fma_f32 v[96:97], v[44:45], v[96:97], v[68:69]
	v_lshlrev_b32_e32 v68, 16, v79
	v_and_b32_e32 v69, 0xffff0000, v79
	v_pk_fma_f32 v[78:79], v[46:47], v[68:69], v[70:71]
	global_load_dwordx2 v[68:69], v[64:65], off offset:512 nt
	s_waitcnt vmcnt(0)
	v_lshlrev_b32_e32 v70, 16, v68
	v_and_b32_e32 v71, 0xffff0000, v68
	v_pk_fma_f32 v[98:99], v[40:41], v[70:71], v[72:73]
	v_lshlrev_b32_e32 v68, 16, v69
	v_and_b32_e32 v69, 0xffff0000, v69
	global_load_dwordx2 v[70:71], v[64:65], off offset:1024 nt
	v_pk_fma_f32 v[100:101], v[42:43], v[68:69], v[74:75]
	global_load_dwordx2 v[74:75], v[64:65], off offset:1536 nt
	s_waitcnt vmcnt(1)
	v_lshlrev_b32_e32 v68, 16, v70
	v_and_b32_e32 v69, 0xffff0000, v70
	v_lshlrev_b32_e32 v70, 16, v71
	v_and_b32_e32 v71, 0xffff0000, v71
	v_pk_fma_f32 v[70:71], v[38:39], v[70:71], v[90:91]
	s_waitcnt vmcnt(0)
	v_lshlrev_b32_e32 v72, 16, v74
	v_and_b32_e32 v73, 0xffff0000, v74
	v_mov_b32_e32 v90, v97
	v_mov_b32_e32 v91, v79
	v_pk_fma_f32 v[68:69], v[36:37], v[68:69], v[88:89]
	v_pk_fma_f32 v[72:73], v[32:33], v[72:73], v[92:93]
	v_mov_b32_e32 v88, v96
	v_mov_b32_e32 v89, v78
	v_pk_mul_f32 v[90:91], v[90:91], v[90:91]
	v_mov_b32_e32 v92, v99
	v_mov_b32_e32 v93, v101
	v_lshlrev_b32_e32 v74, 16, v75
	v_and_b32_e32 v75, 0xffff0000, v75
	v_pk_fma_f32 v[88:89], v[88:89], v[88:89], v[90:91]
	v_mov_b32_e32 v90, v98
	v_mov_b32_e32 v91, v100
	v_pk_mul_f32 v[92:93], v[92:93], v[92:93]
	v_mul_f32_e32 v76, v69, v69
	v_pk_fma_f32 v[74:75], v[34:35], v[74:75], v[94:95]
	v_pk_fma_f32 v[90:91], v[90:91], v[90:91], v[92:93]
	v_pk_fma_f32 v[92:93], v[68:69], v[68:69], v[76:77] op_sel_hi:[1,1,0]
	v_mul_f32_e32 v76, v71, v71
	v_pk_add_f32 v[88:89], v[88:89], v[88:89] op_sel:[0,1] op_sel_hi:[1,0]
	v_pk_add_f32 v[90:91], v[90:91], v[90:91] op_sel:[0,1] op_sel_hi:[1,0]
	v_pk_fma_f32 v[94:95], v[70:71], v[70:71], v[76:77] op_sel_hi:[1,1,0]
	v_pk_mul_f32 v[102:103], v[72:73], v[72:73]
	v_pk_mul_f32 v[104:105], v[74:75], v[74:75]
	v_mov_b32_e32 v89, v102
	v_mov_b32_e32 v91, v103
	v_mov_b32_e32 v93, v104
	v_mov_b32_e32 v95, v105
	v_pk_add_f32 v[88:89], v[88:89], v[90:91]
	v_pk_add_f32 v[90:91], v[92:93], v[94:95]
	s_nop 0
	v_pk_add_f32 v[88:89], v[88:89], v[90:91]
	s_nop 0
	v_add_f32_e32 v76, v88, v89
	ds_bpermute_b32 v87, v80, v76
	s_waitcnt lgkmcnt(0)
	v_add_f32_e32 v76, v76, v87
	ds_bpermute_b32 v87, v81, v76
	s_waitcnt lgkmcnt(0)
	v_add_f32_e32 v76, v76, v87
	ds_bpermute_b32 v87, v82, v76
	s_waitcnt lgkmcnt(0)
	v_add_f32_e32 v76, v76, v87
	ds_bpermute_b32 v87, v83, v76
	s_waitcnt lgkmcnt(0)
	v_add_f32_e32 v76, v76, v87
	ds_bpermute_b32 v87, v84, v76
	s_waitcnt lgkmcnt(0)
	v_add_f32_e32 v76, v76, v87
	ds_bpermute_b32 v87, v85, v76
	s_waitcnt lgkmcnt(0)
	v_add_f32_e32 v76, v76, v87
	v_fmamk_f32 v76, v76, 0x3a800000, v201
	v_cmp_gt_f32_e32 vcc, s16, v76
	v_mul_f32_e32 v87, 0x4b800000, v76
	s_nop 0
	v_cndmask_b32_e32 v76, v76, v87, vcc
	v_rsq_f32_e32 v76, v76
	s_nop 0
	v_mul_f32_e32 v87, 0x45800000, v76
	v_cndmask_b32_e32 v76, v76, v87, vcc
	v_pk_mul_f32 v[78:79], v[78:79], v[76:77] op_sel_hi:[1,0]
	v_pk_mul_f32 v[88:89], v[96:97], v[76:77] op_sel_hi:[1,0]
	v_pk_mul_f32 v[78:79], v[2:3], v[78:79]
	v_pk_mul_f32 v[88:89], v[0:1], v[88:89]
	v_pk_fma_f32 v[78:79], v[48:49], v[78:79], v[18:19]
	v_pk_fma_f32 v[88:89], v[50:51], v[88:89], v[16:17]
	v_pk_mul_f32 v[70:71], v[70:71], v[76:77] op_sel_hi:[1,0]
	v_cvt_pk_bf16_f32 v88, v88, v89
	v_cvt_pk_bf16_f32 v89, v78, v79
	v_add_co_u32_e32 v78, vcc, s15, v64
	v_pk_mul_f32 v[68:69], v[68:69], v[76:77] op_sel_hi:[1,0]
	s_nop 0
	v_addc_co_u32_e32 v79, vcc, -1, v65, vcc
	global_store_dwordx2 v[78:79], v[88:89], off
	v_pk_mul_f32 v[78:79], v[100:101], v[76:77] op_sel_hi:[1,0]
	v_pk_mul_f32 v[88:89], v[98:99], v[76:77] op_sel_hi:[1,0]
	v_pk_mul_f32 v[78:79], v[6:7], v[78:79]
	v_pk_mul_f32 v[88:89], v[4:5], v[88:89]
	v_pk_mul_f32 v[68:69], v[8:9], v[68:69]
	v_pk_mul_f32 v[70:71], v[10:11], v[70:71]
	v_pk_fma_f32 v[90:91], v[52:53], v[78:79], v[22:23]
	v_pk_fma_f32 v[78:79], v[54:55], v[88:89], v[20:21]
	v_add_co_u32_e32 v88, vcc, s60, v64
	v_pk_fma_f32 v[70:71], v[56:57], v[70:71], v[26:27]
	v_pk_fma_f32 v[68:69], v[58:59], v[68:69], v[24:25]
	v_addc_co_u32_e32 v89, vcc, -1, v65, vcc
	v_cvt_pk_bf16_f32 v68, v68, v69
	v_cvt_pk_bf16_f32 v69, v70, v71
	global_store_dwordx2 v[88:89], v[68:69], off offset:-3072
	v_pk_mul_f32 v[68:69], v[74:75], v[76:77] op_sel_hi:[1,0]
	v_pk_mul_f32 v[70:71], v[72:73], v[76:77] op_sel_hi:[1,0]
	v_pk_mul_f32 v[68:69], v[14:15], v[68:69]
	v_pk_mul_f32 v[70:71], v[12:13], v[70:71]
	v_pk_fma_f32 v[68:69], v[60:61], v[68:69], v[30:31]
	v_pk_fma_f32 v[70:71], v[62:63], v[70:71], v[28:29]
	v_cmp_ge_i32_e32 vcc, v86, v77
	v_cvt_pk_bf16_f32 v78, v78, v79
	v_cvt_pk_bf16_f32 v79, v90, v91
	v_cvt_pk_bf16_f32 v70, v70, v71
	v_cvt_pk_bf16_f32 v71, v68, v69
	v_lshl_add_u64 v[64:65], v[64:65], 0, s[2:3]
	s_or_b64 s[12:13], vcc, s[12:13]
	global_store_dwordx2 v[88:89], v[78:79], off offset:-3584
	global_store_dwordx2 v[88:89], v[70:71], off offset:-2560
	s_andn2_b64 exec, exec, s[12:13]
	s_cbranch_execnz .LBB0_116
	s_or_b64 exec, exec, s[12:13]
	s_cmp_lg_u32 s100, 0
	s_cbranch_scc1 .Lnt_done_n1
	s_mov_b32 s100, 1
	s_mov_b64 s[12:13], 0
	v_add_u32_e32 v86, 0x700, v86
	v_add_u32_e32 v77, 0x800, v77
	s_mov_b32 vcc_lo, 0x380000
	s_mov_b32 vcc_hi, 0
	v_lshl_add_u64 v[64:65], v[64:65], 0, vcc
	s_mov_b32 vcc_lo, 0x700000
	v_lshl_add_u64 v[66:67], v[66:67], 0, vcc
	s_branch .LBB0_116

.LBB0_380:
	s_andn2_b64 vcc, exec, s[0:1]
	s_cbranch_vccnz .LBB0_411
	v_readlane_b32 s0, v255, 35
	s_cmp_eq_u32 s0, 0
	s_cbranch_scc0 .LBB0_411
	v_readlane_b32 s0, v255, 25
	v_readlane_b32 s6, v255, 27
	v_readlane_b32 s1, v255, 26
	s_add_u32 s0, s0, 0x1000
	v_readlane_b32 s7, v255, 28
	s_addc_u32 s1, s1, 0
	s_mov_b64 s[2:3], -1
	s_and_b64 vcc, exec, s[6:7]
	s_cbranch_vccz .LBB0_388
	s_waitcnt vmcnt(0)
	v_mov_b32_e32 v0, v200
	s_load_dword s12, s[38:39], 0x0
	v_ashrrev_i32_e32 v2, 6, v0
	v_add_u32_e32 v66, s61, v2
	v_sub_u32_e32 v2, 0, v66
	v_max_i32_e32 v2, v66, v2
	s_waitcnt lgkmcnt(0)
	s_bfe_i32 s19, s12, 0x1d0000
	s_abs_i32 s2, s19
	v_cvt_f32_u32_e32 v1, s2
	v_xor_b32_e32 v3, s19, v66
	s_sub_i32 s3, 0, s2
	v_ashrrev_i32_e32 v65, 31, v3
	v_rcp_iflag_f32_e32 v1, v1
	s_nop 0
	v_mul_f32_e32 v1, 0x4f7ffffe, v1
	v_cvt_u32_f32_e32 v1, v1
	v_mul_lo_u32 v3, s3, v1
	v_mul_hi_u32 v3, v1, v3
	v_add_u32_e32 v1, v1, v3
	v_mul_hi_u32 v1, v2, v1
	v_mul_lo_u32 v3, v1, s2
	v_sub_u32_e32 v2, v2, v3
	v_add_u32_e32 v4, 1, v1
	v_cmp_le_u32_e32 vcc, s2, v2
	v_subrev_u32_e32 v3, s2, v2
	s_nop 0
	v_cndmask_b32_e32 v1, v1, v4, vcc
	v_cndmask_b32_e32 v2, v2, v3, vcc
	v_add_u32_e32 v3, 1, v1
	v_cmp_le_u32_e32 vcc, s2, v2
	s_nop 1
	v_cndmask_b32_e32 v1, v1, v3, vcc
	v_xor_b32_e32 v67, v1, v65
	v_sub_u32_e32 v16, v67, v65
	s_bfe_u32 s100, s61, 0x30003
	v_mov_b32_e32 v16, s100
	v_cmp_gt_i32_e32 vcc, 8, v16
	s_and_saveexec_b64 s[2:3], vcc
	s_mov_b32 s20, 0x800000
	s_cbranch_execz .LBB0_387
	v_lshlrev_b32_e32 v1, 12, v16
	v_mul_lo_u32 v2, v16, s19
	v_add_u32_e32 v3, v1, v66
	v_sub_u32_e32 v64, v3, v2
	v_add_u32_e32 v104, 0x1000, v1
	s_lshr_b32 s101, s61, 6
	s_and_b32 s100, s101, 7
	s_lshr_b32 s101, s101, 3
	s_lshl_b32 s100, s100, 8
	s_lshl_b32 s101, s101, 3
	s_add_i32 s101, s101, s100
	s_bfe_u32 s100, s61, 0x30003
	s_lshl_b32 s100, s100, 12
	s_add_i32 s101, s101, s100
	s_mov_b32 s100, 0
	v_lshrrev_b32_e32 v64, 6, v200
	v_add_u32_e32 v64, s101, v64
	v_and_b32_e32 v104, 0xffffff00, v64
	v_add_u32_e32 v104, 0x100, v104
	v_cmp_lt_i32_e32 vcc, v64, v104
	s_and_b64 exec, exec, vcc
	s_cbranch_execz .LBB0_387
	v_readlane_b32 s6, v255, 29
	v_readlane_b32 s7, v255, 30
	v_readlane_b32 s40, v254, 61
	s_lshl_b64 s[6:7], s[6:7], 2
	v_readlane_b32 s48, v255, 5
	v_readlane_b32 s49, v255, 6
	s_add_u32 s6, s48, s6
	v_and_b32_e32 v100, 63, v0
	s_addc_u32 s7, s49, s7
	v_lshlrev_b32_e32 v128, 4, v100
	v_mov_b64_e32 v[18:19], s[0:1]
	global_load_dwordx4 v[0:3], v128, s[6:7]
	global_load_dwordx4 v[4:7], v128, s[6:7] offset:1024
	global_load_dwordx4 v[8:11], v128, s[6:7] offset:2048
	global_load_dwordx4 v[12:15], v128, s[6:7] offset:3072
	v_mad_i64_i32 v[18:19], s[6:7], v16, s84, v[18:19]
	v_readlane_b32 s6, v255, 25
	v_readlane_b32 s7, v255, 26
	v_lshl_add_u64 v[24:25], v[18:19], 0, v[128:129]
	v_xor_b32_e32 v83, 8, v204
	v_mov_b64_e32 v[18:19], s[6:7]
	v_mad_i64_i32 v[16:17], s[6:7], v16, s84, v[18:19]
	s_mov_b32 s6, 0xfffd5000
	v_lshl_add_u64 v[56:57], v[16:17], 0, v[128:129]
	s_mov_b32 s7, -1
	v_lshl_add_u64 v[48:49], v[56:57], 0, s[6:7]
	s_mov_b32 s6, 0xfffd2000
	s_mov_b32 s7, -1
	v_lshl_add_u64 v[52:53], v[56:57], 0, s[6:7]
	s_mov_b32 s6, 0xfffd5000
	global_load_dwordx4 v[68:71], v[24:25], off
	global_load_dwordx4 v[72:75], v[24:25], off offset:1024
	global_load_dwordx4 v[16:19], v[56:57], off
	global_load_dwordx4 v[20:23], v[56:57], off offset:1024
	global_load_dwordx4 v[76:79], v[24:25], off offset:2048
	global_load_dwordx4 v[96:99], v[24:25], off offset:3072
	s_nop 0
	global_load_dwordx4 v[24:27], v[56:57], off offset:2048
	global_load_dwordx4 v[28:31], v[56:57], off offset:3072
	global_load_dwordx4 v[32:35], v[52:53], off offset:3072
	global_load_dwordx4 v[36:39], v[52:53], off offset:2048
	global_load_dwordx4 v[40:43], v[48:49], off offset:2048
	global_load_dwordx4 v[44:47], v[48:49], off offset:1024
	s_nop 0
	global_load_dwordx4 v[48:51], v[48:49], off offset:3072
	s_nop 0
	global_load_dwordx4 v[52:55], v[52:53], off offset:1024
	v_add_co_u32_e32 v58, vcc, s6, v56
	s_mov_b32 s6, 0xfffd2000
	s_nop 0
	v_addc_co_u32_e32 v59, vcc, -1, v57, vcc
	v_add_co_u32_e32 v60, vcc, s6, v56
	v_sub_u32_e32 v86, v65, v67
	s_nop 0
	v_addc_co_u32_e32 v61, vcc, -1, v57, vcc
	global_load_dwordx4 v[56:59], v[58:59], off
	s_nop 0
	global_load_dwordx4 v[60:63], v[60:61], off
	v_cmp_lt_i32_e32 vcc, v206, v205
	v_lshlrev_b32_e32 v87, 12, v65
	v_ashrrev_i32_e32 v65, 31, v64
	v_cndmask_b32_e32 v80, v204, v206, vcc
	v_cmp_lt_i32_e32 vcc, v207, v205
	s_add_i32 s6, s80, -10
	v_readlane_b32 s41, v254, 62
	v_cndmask_b32_e32 v81, v204, v207, vcc
	v_cmp_lt_i32_e32 vcc, v252, v205
	v_lshlrev_b32_e32 v67, 12, v67
	v_lshlrev_b32_e32 v105, 2, v80
	v_cndmask_b32_e32 v82, v204, v252, vcc
	v_cmp_lt_i32_e32 vcc, v83, v205
	v_lshlrev_b32_e32 v106, 2, v81
	v_lshlrev_b32_e32 v107, 2, v82
	v_cndmask_b32_e32 v83, v204, v83, vcc
	v_cmp_lt_i32_e32 vcc, v210, v205
	v_mul_lo_u32 v82, v86, s19
	v_lshlrev_b64 v[80:81], 12, v[64:65]
	v_cndmask_b32_e32 v84, v204, v210, vcc
	v_cmp_lt_i32_e32 vcc, v211, v205
	s_cmp_lt_u32 s6, 9
	v_lshlrev_b64 v[64:65], 11, v[64:65]
	v_cndmask_b32_e32 v85, v204, v211, vcc
	v_add3_u32 v66, v66, v82, v67
	s_cselect_b32 s7, s41, s77
	s_cselect_b32 s6, s40, s76
	s_mov_b32 s15, 0
	s_mov_b32 s14, 32
	v_lshl_or_b32 v64, v100, 3, v64
	v_lshlrev_b32_e32 v108, 2, v83
	v_lshlrev_b32_e32 v109, 2, v84
	v_lshlrev_b32_e32 v110, 2, v85
	v_or_b32_e32 v80, v80, v128
	v_sub_u32_e32 v111, v66, v87
	v_lshrrev_b32_e32 v111, 6, v200
	v_add_u32_e32 v111, s101, v111
	s_lshl_b64 s[12:13], s[14:15], 12
	s_lshl_b64 s[14:15], s[14:15], 11
	s_mov_b64 s[16:17], 0
	v_readlane_b32 s42, v254, 63
	v_readlane_b32 s43, v255, 0
	v_readlane_b32 s44, v255, 1
	v_readlane_b32 s45, v255, 2
	v_readlane_b32 s46, v255, 3
	v_readlane_b32 s47, v255, 4
	v_readlane_b32 s50, v255, 7
	v_readlane_b32 s51, v255, 8
	v_readlane_b32 s52, v255, 9
	v_readlane_b32 s53, v255, 10
	v_readlane_b32 s54, v255, 11
	v_readlane_b32 s55, v255, 12
	s_waitcnt vmcnt(15)
	v_pk_add_f32 v[82:83], v[70:71], 1.0 op_sel_hi:[1,0]
	v_pk_add_f32 v[84:85], v[68:69], 1.0 op_sel_hi:[1,0]
	s_waitcnt vmcnt(14)
	v_pk_add_f32 v[86:87], v[74:75], 1.0 op_sel_hi:[1,0]
	v_pk_add_f32 v[88:89], v[72:73], 1.0 op_sel_hi:[1,0]
	s_waitcnt vmcnt(11)
	v_pk_add_f32 v[90:91], v[78:79], 1.0 op_sel_hi:[1,0]
	v_pk_add_f32 v[92:93], v[76:77], 1.0 op_sel_hi:[1,0]
	s_waitcnt vmcnt(10)
	v_pk_add_f32 v[94:95], v[98:99], 1.0 op_sel_hi:[1,0]
	v_pk_add_f32 v[96:97], v[96:97], 1.0 op_sel_hi:[1,0]
	v_lshl_add_u64 v[98:99], s[4:5], 0, v[64:65]
.LBB0_386:
	v_add_co_u32_e32 v100, vcc, 0xec800000, v98
	v_lshl_add_u64 v[76:77], s[6:7], 0, v[80:81]
	s_nop 0
	v_addc_co_u32_e32 v101, vcc, -1, v99, vcc
	global_load_dwordx4 v[64:67], v[76:77], off nt
	global_load_dwordx4 v[68:71], v[76:77], off offset:1024 nt
	global_load_dwordx4 v[72:75], v[76:77], off offset:2048 nt
	s_nop 0
	global_load_dwordx4 v[76:79], v[76:77], off offset:3072 nt
	s_nop 0
	global_load_dwordx2 v[102:103], v[98:99], off nt
	global_load_dwordx2 v[112:113], v[98:99], off offset:512 nt
	global_load_dwordx2 v[114:115], v[98:99], off offset:1024 nt
	global_load_dwordx2 v[116:117], v[98:99], off offset:1536 nt
	global_load_dwordx2 v[118:119], v[100:101], off nt
	v_add_u32_e32 v111, 32, v111
	s_waitcnt vmcnt(4)
	v_lshlrev_b32_e32 v120, 16, v102
	v_and_b32_e32 v121, 0xffff0000, v102
	v_lshlrev_b32_e32 v102, 16, v103
	v_and_b32_e32 v103, 0xffff0000, v103
	v_pk_fma_f32 v[66:67], v[62:63], v[102:103], v[66:67]
	s_waitcnt vmcnt(0)
	v_lshlrev_b32_e32 v102, 16, v119
	v_and_b32_e32 v103, 0xffff0000, v119
	v_pk_fma_f32 v[66:67], v[58:59], v[102:103], v[66:67]
	v_add_co_u32_e32 v102, vcc, s60, v98
	v_pk_fma_f32 v[64:65], v[60:61], v[120:121], v[64:65]
	s_nop 0
	v_addc_co_u32_e32 v103, vcc, -1, v99, vcc
	v_lshlrev_b32_e32 v120, 16, v118
	v_and_b32_e32 v121, 0xffff0000, v118
	global_load_dwordx2 v[118:119], v[102:103], off offset:-3584 nt
	v_pk_fma_f32 v[64:65], v[56:57], v[120:121], v[64:65]
	v_lshlrev_b32_e32 v120, 16, v112
	v_and_b32_e32 v121, 0xffff0000, v112
	v_lshlrev_b32_e32 v112, 16, v113
	v_and_b32_e32 v113, 0xffff0000, v113
	v_pk_fma_f32 v[70:71], v[54:55], v[112:113], v[70:71]
	v_pk_fma_f32 v[68:69], v[52:53], v[120:121], v[68:69]
	v_lshl_add_u64 v[98:99], v[98:99], 0, s[14:15]
	s_waitcnt vmcnt(0)
	v_lshlrev_b32_e32 v112, 16, v119
	v_and_b32_e32 v113, 0xffff0000, v119
	v_pk_fma_f32 v[70:71], v[46:47], v[112:113], v[70:71]
	global_load_dwordx2 v[112:113], v[102:103], off offset:-3072 nt
	v_lshlrev_b32_e32 v120, 16, v118
	v_and_b32_e32 v121, 0xffff0000, v118
	v_lshlrev_b32_e32 v118, 16, v114
	v_and_b32_e32 v119, 0xffff0000, v114
	v_lshlrev_b32_e32 v114, 16, v115
	v_and_b32_e32 v115, 0xffff0000, v115
	v_pk_fma_f32 v[72:73], v[36:37], v[118:119], v[72:73]
	v_pk_fma_f32 v[74:75], v[38:39], v[114:115], v[74:75]
	v_lshlrev_b32_e32 v114, 16, v116
	v_and_b32_e32 v115, 0xffff0000, v116
	v_pk_fma_f32 v[76:77], v[32:33], v[114:115], v[76:77]
	v_pk_fma_f32 v[68:69], v[44:45], v[120:121], v[68:69]
	s_waitcnt vmcnt(0)
	v_lshlrev_b32_e32 v118, 16, v112
	v_and_b32_e32 v119, 0xffff0000, v112
	v_lshlrev_b32_e32 v112, 16, v113
	v_and_b32_e32 v113, 0xffff0000, v113
	v_pk_fma_f32 v[74:75], v[42:43], v[112:113], v[74:75]
	global_load_dwordx2 v[112:113], v[102:103], off offset:-2560 nt
	v_mov_b32_e32 v116, v69
	v_pk_fma_f32 v[72:73], v[40:41], v[118:119], v[72:73]
	v_mul_f32_e32 v118, v75, v75
	v_pk_fma_f32 v[118:119], v[74:75], v[74:75], v[118:119] op_sel_hi:[1,1,0]
	s_waitcnt vmcnt(0)
	v_lshlrev_b32_e32 v114, 16, v112
	v_and_b32_e32 v115, 0xffff0000, v112
	v_pk_fma_f32 v[76:77], v[48:49], v[114:115], v[76:77]
	v_lshlrev_b32_e32 v114, 16, v117
	v_and_b32_e32 v115, 0xffff0000, v117
	v_pk_fma_f32 v[78:79], v[34:35], v[114:115], v[78:79]
	v_lshlrev_b32_e32 v112, 16, v113
	v_and_b32_e32 v113, 0xffff0000, v113
	v_mov_b32_e32 v114, v65
	v_mov_b32_e32 v115, v67
	v_pk_fma_f32 v[78:79], v[50:51], v[112:113], v[78:79]
	v_mov_b32_e32 v112, v64
	v_mov_b32_e32 v113, v66
	v_pk_mul_f32 v[114:115], v[114:115], v[114:115]
	v_mov_b32_e32 v117, v71
	v_pk_fma_f32 v[112:113], v[112:113], v[112:113], v[114:115]
	v_mov_b32_e32 v114, v68
	v_mov_b32_e32 v115, v70
	v_pk_mul_f32 v[116:117], v[116:117], v[116:117]
	v_pk_add_f32 v[112:113], v[112:113], v[112:113] op_sel:[0,1] op_sel_hi:[1,0]
	v_pk_fma_f32 v[114:115], v[114:115], v[114:115], v[116:117]
	v_mul_f32_e32 v116, v73, v73
	v_pk_add_f32 v[114:115], v[114:115], v[114:115] op_sel:[0,1] op_sel_hi:[1,0]
	v_pk_fma_f32 v[116:117], v[72:73], v[72:73], v[116:117] op_sel_hi:[1,1,0]
	v_pk_mul_f32 v[120:121], v[76:77], v[76:77]
	v_pk_mul_f32 v[122:123], v[78:79], v[78:79]
	v_mov_b32_e32 v113, v120
	v_mov_b32_e32 v115, v121
	v_mov_b32_e32 v117, v122
	v_mov_b32_e32 v119, v123
	v_pk_add_f32 v[112:113], v[112:113], v[114:115]
	v_pk_add_f32 v[114:115], v[116:117], v[118:119]
	s_nop 0
	v_pk_add_f32 v[112:113], v[112:113], v[114:115]
	s_nop 0
	v_add_f32_e32 v112, v112, v113
	ds_bpermute_b32 v113, v105, v112
	s_waitcnt lgkmcnt(0)
	v_add_f32_e32 v112, v112, v113
	ds_bpermute_b32 v113, v106, v112
	s_waitcnt lgkmcnt(0)
	v_add_f32_e32 v112, v112, v113
	ds_bpermute_b32 v113, v107, v112
	s_waitcnt lgkmcnt(0)
	v_add_f32_e32 v112, v112, v113
	ds_bpermute_b32 v113, v108, v112
	s_waitcnt lgkmcnt(0)
	v_add_f32_e32 v112, v112, v113
	ds_bpermute_b32 v113, v109, v112
	s_waitcnt lgkmcnt(0)
	v_add_f32_e32 v112, v112, v113
	ds_bpermute_b32 v113, v110, v112
	s_waitcnt lgkmcnt(0)
	v_add_f32_e32 v112, v112, v113
	v_fmamk_f32 v112, v112, 0x3a800000, v201
	v_cmp_gt_f32_e32 vcc, s20, v112
	v_mul_f32_e32 v113, 0x4b800000, v112
	s_nop 0
	v_cndmask_b32_e32 v112, v112, v113, vcc
	v_rsq_f32_e32 v114, v112
	v_lshl_add_u64 v[112:113], s[76:77], 0, v[80:81]
	global_store_dwordx4 v[112:113], v[64:67], off nt
	global_store_dwordx4 v[112:113], v[68:71], off offset:1024 nt
	global_store_dwordx4 v[112:113], v[72:75], off offset:2048 nt
	global_store_dwordx4 v[112:113], v[76:79], off offset:3072 nt
	v_lshl_add_u64 v[80:81], v[80:81], 0, s[12:13]
	v_mul_f32_e32 v115, 0x45800000, v114
	v_cndmask_b32_e32 v112, v114, v115, vcc
	v_pk_mul_f32 v[66:67], v[66:67], v[112:113] op_sel_hi:[1,0]
	v_pk_mul_f32 v[64:65], v[64:65], v[112:113] op_sel_hi:[1,0]
	v_pk_mul_f32 v[66:67], v[2:3], v[66:67]
	v_pk_mul_f32 v[64:65], v[0:1], v[64:65]
	v_pk_fma_f32 v[66:67], v[82:83], v[66:67], v[18:19]
	v_pk_fma_f32 v[64:65], v[84:85], v[64:65], v[16:17]
	v_cmp_ge_i32_e32 vcc, v111, v104
	v_cvt_pk_bf16_f32 v64, v64, v65
	v_cvt_pk_bf16_f32 v65, v66, v67
	global_store_dwordx2 v[100:101], v[64:65], off
	v_pk_mul_f32 v[64:65], v[70:71], v[112:113] op_sel_hi:[1,0]
	v_pk_mul_f32 v[66:67], v[68:69], v[112:113] op_sel_hi:[1,0]
	v_pk_mul_f32 v[64:65], v[6:7], v[64:65]
	v_pk_mul_f32 v[66:67], v[4:5], v[66:67]
	v_pk_fma_f32 v[64:65], v[86:87], v[64:65], v[22:23]
	v_pk_fma_f32 v[66:67], v[88:89], v[66:67], v[20:21]
	s_or_b64 s[16:17], vcc, s[16:17]
	v_cvt_pk_bf16_f32 v66, v66, v67
	v_cvt_pk_bf16_f32 v67, v64, v65
	global_store_dwordx2 v[102:103], v[66:67], off offset:-3584
	v_pk_mul_f32 v[64:65], v[74:75], v[112:113] op_sel_hi:[1,0]
	v_pk_mul_f32 v[66:67], v[72:73], v[112:113] op_sel_hi:[1,0]
	v_pk_mul_f32 v[64:65], v[10:11], v[64:65]
	v_pk_mul_f32 v[66:67], v[8:9], v[66:67]
	v_pk_fma_f32 v[64:65], v[90:91], v[64:65], v[26:27]
	v_pk_fma_f32 v[66:67], v[92:93], v[66:67], v[24:25]
	s_nop 0
	v_cvt_pk_bf16_f32 v66, v66, v67
	v_cvt_pk_bf16_f32 v67, v64, v65
	global_store_dwordx2 v[102:103], v[66:67], off offset:-3072
	v_pk_mul_f32 v[64:65], v[78:79], v[112:113] op_sel_hi:[1,0]
	v_pk_mul_f32 v[66:67], v[76:77], v[112:113] op_sel_hi:[1,0]
	v_pk_mul_f32 v[64:65], v[14:15], v[64:65]
	v_pk_mul_f32 v[66:67], v[12:13], v[66:67]
	v_pk_fma_f32 v[64:65], v[94:95], v[64:65], v[30:31]
	v_pk_fma_f32 v[66:67], v[96:97], v[66:67], v[28:29]
	s_nop 0
	v_cvt_pk_bf16_f32 v66, v66, v67
	v_cvt_pk_bf16_f32 v67, v64, v65
	global_store_dwordx2 v[102:103], v[66:67], off offset:-2560
	s_andn2_b64 exec, exec, s[16:17]
	s_cbranch_execnz .LBB0_386
	s_or_b64 exec, exec, s[16:17]
	s_cmp_lg_u32 s100, 0
	s_cbranch_scc1 .Lnt_done_n2
	s_mov_b32 s100, 1
	s_mov_b64 s[16:17], 0
	v_add_u32_e32 v111, 0x700, v111
	v_add_u32_e32 v104, 0x800, v104
	s_mov_b32 vcc_lo, 0x380000
	s_mov_b32 vcc_hi, 0
	v_lshl_add_u64 v[98:99], v[98:99], 0, vcc
	s_mov_b32 vcc_lo, 0x700000
	v_lshl_add_u64 v[80:81], v[80:81], 0, vcc
	s_branch .LBB0_386
.Lnt_done_n2:
.LBB0_387:
	s_or_b64 exec, exec, s[2:3]
	s_mov_b64 s[2:3], 0
